# nt hint on once-read loads only (weight reads of transposes and adaLN GEMV, final-norm loads); final-norm stores back to default
# baseline (speedup 1.0000x reference)
.Lnm_fin_loop:
	s_add_i32 s8, s4, -15
	s_ashr_i32 s9, s8, 31
	s_lshl_b64 s[10:11], s[8:9], 13
	s_mov_b64 s[24:25], s[10:11]
	v_lshl_add_u64 v[124:125], v[68:69], 0, s[10:11]
	global_load_dwordx4 v[4:7], v[124:125], off nt
	s_add_u32 s10, s10, 0x2000
	s_addc_u32 s11, s11, 0
	v_lshl_add_u64 v[124:125], v[68:69], 0, s[10:11]
	global_load_dwordx4 v[8:11], v[124:125], off nt
	s_add_u32 s10, s10, 0x2000
	s_addc_u32 s11, s11, 0
	v_lshl_add_u64 v[124:125], v[68:69], 0, s[10:11]
	global_load_dwordx4 v[12:15], v[124:125], off nt
	s_add_u32 s10, s10, 0x2000
	s_addc_u32 s11, s11, 0
	v_lshl_add_u64 v[124:125], v[68:69], 0, s[10:11]
	global_load_dwordx4 v[16:19], v[124:125], off nt
	s_add_u32 s10, s10, 0x2000
	s_addc_u32 s11, s11, 0
	v_lshl_add_u64 v[124:125], v[68:69], 0, s[10:11]
	global_load_dwordx4 v[20:23], v[124:125], off nt
	s_add_u32 s10, s10, 0x2000
	s_addc_u32 s11, s11, 0
	v_lshl_add_u64 v[124:125], v[68:69], 0, s[10:11]
	global_load_dwordx4 v[24:27], v[124:125], off nt
	s_add_u32 s10, s10, 0x2000
	s_addc_u32 s11, s11, 0
	v_lshl_add_u64 v[124:125], v[68:69], 0, s[10:11]
	global_load_dwordx4 v[28:31], v[124:125], off nt
	s_add_u32 s10, s10, 0x2000
	s_addc_u32 s11, s11, 0
	v_lshl_add_u64 v[124:125], v[68:69], 0, s[10:11]
	global_load_dwordx4 v[32:35], v[124:125], off nt
	s_add_u32 s10, s10, 0x2000
	s_addc_u32 s11, s11, 0
	v_lshl_add_u64 v[124:125], v[68:69], 0, s[10:11]
	global_load_dwordx4 v[36:39], v[124:125], off nt
	s_add_u32 s10, s10, 0x2000
	s_addc_u32 s11, s11, 0
	v_lshl_add_u64 v[124:125], v[68:69], 0, s[10:11]
	global_load_dwordx4 v[40:43], v[124:125], off nt
	s_add_u32 s10, s10, 0x2000
	s_addc_u32 s11, s11, 0
	v_lshl_add_u64 v[124:125], v[68:69], 0, s[10:11]
	global_load_dwordx4 v[44:47], v[124:125], off nt
	s_add_u32 s10, s10, 0x2000
	s_addc_u32 s11, s11, 0
	v_lshl_add_u64 v[124:125], v[68:69], 0, s[10:11]
	global_load_dwordx4 v[48:51], v[124:125], off nt
	s_add_u32 s10, s10, 0x2000
	s_addc_u32 s11, s11, 0
	v_lshl_add_u64 v[124:125], v[68:69], 0, s[10:11]
	global_load_dwordx4 v[52:55], v[124:125], off nt
	s_add_u32 s10, s10, 0x2000
	s_addc_u32 s11, s11, 0
	v_lshl_add_u64 v[124:125], v[68:69], 0, s[10:11]
	global_load_dwordx4 v[56:59], v[124:125], off nt
	s_add_u32 s10, s10, 0x2000
	s_addc_u32 s11, s11, 0
	v_lshl_add_u64 v[124:125], v[68:69], 0, s[10:11]
	global_load_dwordx4 v[60:63], v[124:125], off nt
	s_add_u32 s10, s10, 0x2000
	s_addc_u32 s11, s11, 0
	v_lshl_add_u64 v[124:125], v[68:69], 0, s[10:11]
	global_load_dwordx4 v[64:67], v[124:125], off nt
	s_waitcnt vmcnt(15)
	v_mul_f32_e32 v84, v5, v5
	v_mul_f32_e32 v100, v7, v7
	v_fmac_f32_e32 v84, v4, v4
	v_fmac_f32_e32 v100, v6, v6
	v_add_f32_e32 v84, v84, v100
	s_waitcnt vmcnt(14)
	v_mul_f32_e32 v85, v9, v9
	v_mul_f32_e32 v101, v11, v11
	v_fmac_f32_e32 v85, v8, v8
	v_fmac_f32_e32 v101, v10, v10
	v_add_f32_e32 v85, v85, v101
	s_waitcnt vmcnt(13)
	v_mul_f32_e32 v86, v13, v13
	v_mul_f32_e32 v102, v15, v15
	v_fmac_f32_e32 v86, v12, v12
	v_fmac_f32_e32 v102, v14, v14
	v_add_f32_e32 v86, v86, v102
	s_waitcnt vmcnt(12)
	v_mul_f32_e32 v87, v17, v17
	v_mul_f32_e32 v103, v19, v19
	v_fmac_f32_e32 v87, v16, v16
	v_fmac_f32_e32 v103, v18, v18
	v_add_f32_e32 v87, v87, v103
	s_waitcnt vmcnt(11)
	v_mul_f32_e32 v88, v21, v21
	v_mul_f32_e32 v104, v23, v23
	v_fmac_f32_e32 v88, v20, v20
	v_fmac_f32_e32 v104, v22, v22
	v_add_f32_e32 v88, v88, v104
	s_waitcnt vmcnt(10)
	v_mul_f32_e32 v89, v25, v25
	v_mul_f32_e32 v105, v27, v27
	v_fmac_f32_e32 v89, v24, v24
	v_fmac_f32_e32 v105, v26, v26
	v_add_f32_e32 v89, v89, v105
	s_waitcnt vmcnt(9)
	v_mul_f32_e32 v90, v29, v29
	v_mul_f32_e32 v106, v31, v31
	v_fmac_f32_e32 v90, v28, v28
	v_fmac_f32_e32 v106, v30, v30
	v_add_f32_e32 v90, v90, v106
	s_waitcnt vmcnt(8)
	v_mul_f32_e32 v91, v33, v33
	v_mul_f32_e32 v107, v35, v35
	v_fmac_f32_e32 v91, v32, v32
	v_fmac_f32_e32 v107, v34, v34
	v_add_f32_e32 v91, v91, v107
	s_waitcnt vmcnt(7)
	v_mul_f32_e32 v92, v37, v37
	v_mul_f32_e32 v108, v39, v39
	v_fmac_f32_e32 v92, v36, v36
	v_fmac_f32_e32 v108, v38, v38
	v_add_f32_e32 v92, v92, v108
	s_waitcnt vmcnt(6)
	v_mul_f32_e32 v93, v41, v41
	v_mul_f32_e32 v109, v43, v43
	v_fmac_f32_e32 v93, v40, v40
	v_fmac_f32_e32 v109, v42, v42
	v_add_f32_e32 v93, v93, v109
	s_waitcnt vmcnt(5)
	v_mul_f32_e32 v94, v45, v45
	v_mul_f32_e32 v110, v47, v47
	v_fmac_f32_e32 v94, v44, v44
	v_fmac_f32_e32 v110, v46, v46
	v_add_f32_e32 v94, v94, v110
	s_waitcnt vmcnt(4)
	v_mul_f32_e32 v95, v49, v49
	v_mul_f32_e32 v111, v51, v51
	v_fmac_f32_e32 v95, v48, v48
	v_fmac_f32_e32 v111, v50, v50
	v_add_f32_e32 v95, v95, v111
	s_waitcnt vmcnt(3)
	v_mul_f32_e32 v96, v53, v53
	v_mul_f32_e32 v112, v55, v55
	v_fmac_f32_e32 v96, v52, v52
	v_fmac_f32_e32 v112, v54, v54
	v_add_f32_e32 v96, v96, v112
	s_waitcnt vmcnt(2)
	v_mul_f32_e32 v97, v57, v57
	v_mul_f32_e32 v113, v59, v59
	v_fmac_f32_e32 v97, v56, v56
	v_fmac_f32_e32 v113, v58, v58
	v_add_f32_e32 v97, v97, v113
	s_waitcnt vmcnt(1)
	v_mul_f32_e32 v98, v61, v61
	v_mul_f32_e32 v114, v63, v63
	v_fmac_f32_e32 v98, v60, v60
	v_fmac_f32_e32 v114, v62, v62
	v_add_f32_e32 v98, v98, v114
	s_waitcnt vmcnt(0)
	v_mul_f32_e32 v99, v65, v65
	v_mul_f32_e32 v115, v67, v67
	v_fmac_f32_e32 v99, v64, v64
	v_fmac_f32_e32 v115, v66, v66
	v_add_f32_e32 v99, v99, v115
	ds_bpermute_b32 v100, v73, v84
	ds_bpermute_b32 v101, v73, v85
	ds_bpermute_b32 v102, v73, v86
	ds_bpermute_b32 v103, v73, v87
	ds_bpermute_b32 v104, v73, v88
	ds_bpermute_b32 v105, v73, v89
	ds_bpermute_b32 v106, v73, v90
	ds_bpermute_b32 v107, v73, v91
	ds_bpermute_b32 v108, v73, v92
	ds_bpermute_b32 v109, v73, v93
	ds_bpermute_b32 v110, v73, v94
	ds_bpermute_b32 v111, v73, v95
	ds_bpermute_b32 v112, v73, v96
	ds_bpermute_b32 v113, v73, v97
	ds_bpermute_b32 v114, v73, v98
	ds_bpermute_b32 v115, v73, v99
	s_waitcnt lgkmcnt(15)
	v_add_f32_e32 v84, v84, v100
	s_waitcnt lgkmcnt(14)
	v_add_f32_e32 v85, v85, v101
	s_waitcnt lgkmcnt(13)
	v_add_f32_e32 v86, v86, v102
	s_waitcnt lgkmcnt(12)
	v_add_f32_e32 v87, v87, v103
	s_waitcnt lgkmcnt(11)
	v_add_f32_e32 v88, v88, v104
	s_waitcnt lgkmcnt(10)
	v_add_f32_e32 v89, v89, v105
	s_waitcnt lgkmcnt(9)
	v_add_f32_e32 v90, v90, v106
	s_waitcnt lgkmcnt(8)
	v_add_f32_e32 v91, v91, v107
	s_waitcnt lgkmcnt(7)
	v_add_f32_e32 v92, v92, v108
	s_waitcnt lgkmcnt(6)
	v_add_f32_e32 v93, v93, v109
	s_waitcnt lgkmcnt(5)
	v_add_f32_e32 v94, v94, v110
	s_waitcnt lgkmcnt(4)
	v_add_f32_e32 v95, v95, v111
	s_waitcnt lgkmcnt(3)
	v_add_f32_e32 v96, v96, v112
	s_waitcnt lgkmcnt(2)
	v_add_f32_e32 v97, v97, v113
	s_waitcnt lgkmcnt(1)
	v_add_f32_e32 v98, v98, v114
	s_waitcnt lgkmcnt(0)
	v_add_f32_e32 v99, v99, v115
	ds_bpermute_b32 v100, v74, v84
	ds_bpermute_b32 v101, v74, v85
	ds_bpermute_b32 v102, v74, v86
	ds_bpermute_b32 v103, v74, v87
	ds_bpermute_b32 v104, v74, v88
	ds_bpermute_b32 v105, v74, v89
	ds_bpermute_b32 v106, v74, v90
	ds_bpermute_b32 v107, v74, v91
	ds_bpermute_b32 v108, v74, v92
	ds_bpermute_b32 v109, v74, v93
	ds_bpermute_b32 v110, v74, v94
	ds_bpermute_b32 v111, v74, v95
	ds_bpermute_b32 v112, v74, v96
	ds_bpermute_b32 v113, v74, v97
	ds_bpermute_b32 v114, v74, v98
	ds_bpermute_b32 v115, v74, v99
	s_waitcnt lgkmcnt(15)
	v_add_f32_e32 v84, v84, v100
	s_waitcnt lgkmcnt(14)
	v_add_f32_e32 v85, v85, v101
	s_waitcnt lgkmcnt(13)
	v_add_f32_e32 v86, v86, v102
	s_waitcnt lgkmcnt(12)
	v_add_f32_e32 v87, v87, v103
	s_waitcnt lgkmcnt(11)
	v_add_f32_e32 v88, v88, v104
	s_waitcnt lgkmcnt(10)
	v_add_f32_e32 v89, v89, v105
	s_waitcnt lgkmcnt(9)
	v_add_f32_e32 v90, v90, v106
	s_waitcnt lgkmcnt(8)
	v_add_f32_e32 v91, v91, v107
	s_waitcnt lgkmcnt(7)
	v_add_f32_e32 v92, v92, v108
	s_waitcnt lgkmcnt(6)
	v_add_f32_e32 v93, v93, v109
	s_waitcnt lgkmcnt(5)
	v_add_f32_e32 v94, v94, v110
	s_waitcnt lgkmcnt(4)
	v_add_f32_e32 v95, v95, v111
	s_waitcnt lgkmcnt(3)
	v_add_f32_e32 v96, v96, v112
	s_waitcnt lgkmcnt(2)
	v_add_f32_e32 v97, v97, v113
	s_waitcnt lgkmcnt(1)
	v_add_f32_e32 v98, v98, v114
	s_waitcnt lgkmcnt(0)
	v_add_f32_e32 v99, v99, v115
	ds_bpermute_b32 v100, v75, v84
	ds_bpermute_b32 v101, v75, v85
	ds_bpermute_b32 v102, v75, v86
	ds_bpermute_b32 v103, v75, v87
	ds_bpermute_b32 v104, v75, v88
	ds_bpermute_b32 v105, v75, v89
	ds_bpermute_b32 v106, v75, v90
	ds_bpermute_b32 v107, v75, v91
	ds_bpermute_b32 v108, v75, v92
	ds_bpermute_b32 v109, v75, v93
	ds_bpermute_b32 v110, v75, v94
	ds_bpermute_b32 v111, v75, v95
	ds_bpermute_b32 v112, v75, v96
	ds_bpermute_b32 v113, v75, v97
	ds_bpermute_b32 v114, v75, v98
	ds_bpermute_b32 v115, v75, v99
	s_waitcnt lgkmcnt(15)
	v_add_f32_e32 v84, v84, v100
	s_waitcnt lgkmcnt(14)
	v_add_f32_e32 v85, v85, v101
	s_waitcnt lgkmcnt(13)
	v_add_f32_e32 v86, v86, v102
	s_waitcnt lgkmcnt(12)
	v_add_f32_e32 v87, v87, v103
	s_waitcnt lgkmcnt(11)
	v_add_f32_e32 v88, v88, v104
	s_waitcnt lgkmcnt(10)
	v_add_f32_e32 v89, v89, v105
	s_waitcnt lgkmcnt(9)
	v_add_f32_e32 v90, v90, v106
	s_waitcnt lgkmcnt(8)
	v_add_f32_e32 v91, v91, v107
	s_waitcnt lgkmcnt(7)
	v_add_f32_e32 v92, v92, v108
	s_waitcnt lgkmcnt(6)
	v_add_f32_e32 v93, v93, v109
	s_waitcnt lgkmcnt(5)
	v_add_f32_e32 v94, v94, v110
	s_waitcnt lgkmcnt(4)
	v_add_f32_e32 v95, v95, v111
	s_waitcnt lgkmcnt(3)
	v_add_f32_e32 v96, v96, v112
	s_waitcnt lgkmcnt(2)
	v_add_f32_e32 v97, v97, v113
	s_waitcnt lgkmcnt(1)
	v_add_f32_e32 v98, v98, v114
	s_waitcnt lgkmcnt(0)
	v_add_f32_e32 v99, v99, v115
	ds_bpermute_b32 v100, v76, v84
	ds_bpermute_b32 v101, v76, v85
	ds_bpermute_b32 v102, v76, v86
	ds_bpermute_b32 v103, v76, v87
	ds_bpermute_b32 v104, v76, v88
	ds_bpermute_b32 v105, v76, v89
	ds_bpermute_b32 v106, v76, v90
	ds_bpermute_b32 v107, v76, v91
	ds_bpermute_b32 v108, v76, v92
	ds_bpermute_b32 v109, v76, v93
	ds_bpermute_b32 v110, v76, v94
	ds_bpermute_b32 v111, v76, v95
	ds_bpermute_b32 v112, v76, v96
	ds_bpermute_b32 v113, v76, v97
	ds_bpermute_b32 v114, v76, v98
	ds_bpermute_b32 v115, v76, v99
	s_waitcnt lgkmcnt(15)
	v_add_f32_e32 v84, v84, v100
	s_waitcnt lgkmcnt(14)
	v_add_f32_e32 v85, v85, v101
	s_waitcnt lgkmcnt(13)
	v_add_f32_e32 v86, v86, v102
	s_waitcnt lgkmcnt(12)
	v_add_f32_e32 v87, v87, v103
	s_waitcnt lgkmcnt(11)
	v_add_f32_e32 v88, v88, v104
	s_waitcnt lgkmcnt(10)
	v_add_f32_e32 v89, v89, v105
	s_waitcnt lgkmcnt(9)
	v_add_f32_e32 v90, v90, v106
	s_waitcnt lgkmcnt(8)
	v_add_f32_e32 v91, v91, v107
	s_waitcnt lgkmcnt(7)
	v_add_f32_e32 v92, v92, v108
	s_waitcnt lgkmcnt(6)
	v_add_f32_e32 v93, v93, v109
	s_waitcnt lgkmcnt(5)
	v_add_f32_e32 v94, v94, v110
	s_waitcnt lgkmcnt(4)
	v_add_f32_e32 v95, v95, v111
	s_waitcnt lgkmcnt(3)
	v_add_f32_e32 v96, v96, v112
	s_waitcnt lgkmcnt(2)
	v_add_f32_e32 v97, v97, v113
	s_waitcnt lgkmcnt(1)
	v_add_f32_e32 v98, v98, v114
	s_waitcnt lgkmcnt(0)
	v_add_f32_e32 v99, v99, v115
	ds_bpermute_b32 v100, v77, v84
	ds_bpermute_b32 v101, v77, v85
	ds_bpermute_b32 v102, v77, v86
	ds_bpermute_b32 v103, v77, v87
	ds_bpermute_b32 v104, v77, v88
	ds_bpermute_b32 v105, v77, v89
	ds_bpermute_b32 v106, v77, v90
	ds_bpermute_b32 v107, v77, v91
	ds_bpermute_b32 v108, v77, v92
	ds_bpermute_b32 v109, v77, v93
	ds_bpermute_b32 v110, v77, v94
	ds_bpermute_b32 v111, v77, v95
	ds_bpermute_b32 v112, v77, v96
	ds_bpermute_b32 v113, v77, v97
	ds_bpermute_b32 v114, v77, v98
	ds_bpermute_b32 v115, v77, v99
	s_waitcnt lgkmcnt(15)
	v_add_f32_e32 v84, v84, v100
	s_waitcnt lgkmcnt(14)
	v_add_f32_e32 v85, v85, v101
	s_waitcnt lgkmcnt(13)
	v_add_f32_e32 v86, v86, v102
	s_waitcnt lgkmcnt(12)
	v_add_f32_e32 v87, v87, v103
	s_waitcnt lgkmcnt(11)
	v_add_f32_e32 v88, v88, v104
	s_waitcnt lgkmcnt(10)
	v_add_f32_e32 v89, v89, v105
	s_waitcnt lgkmcnt(9)
	v_add_f32_e32 v90, v90, v106
	s_waitcnt lgkmcnt(8)
	v_add_f32_e32 v91, v91, v107
	s_waitcnt lgkmcnt(7)
	v_add_f32_e32 v92, v92, v108
	s_waitcnt lgkmcnt(6)
	v_add_f32_e32 v93, v93, v109
	s_waitcnt lgkmcnt(5)
	v_add_f32_e32 v94, v94, v110
	s_waitcnt lgkmcnt(4)
	v_add_f32_e32 v95, v95, v111
	s_waitcnt lgkmcnt(3)
	v_add_f32_e32 v96, v96, v112
	s_waitcnt lgkmcnt(2)
	v_add_f32_e32 v97, v97, v113
	s_waitcnt lgkmcnt(1)
	v_add_f32_e32 v98, v98, v114
	s_waitcnt lgkmcnt(0)
	v_add_f32_e32 v99, v99, v115
	ds_bpermute_b32 v100, v78, v84
	ds_bpermute_b32 v101, v78, v85
	ds_bpermute_b32 v102, v78, v86
	ds_bpermute_b32 v103, v78, v87
	ds_bpermute_b32 v104, v78, v88
	ds_bpermute_b32 v105, v78, v89
	ds_bpermute_b32 v106, v78, v90
	ds_bpermute_b32 v107, v78, v91
	ds_bpermute_b32 v108, v78, v92
	ds_bpermute_b32 v109, v78, v93
	ds_bpermute_b32 v110, v78, v94
	ds_bpermute_b32 v111, v78, v95
	ds_bpermute_b32 v112, v78, v96
	ds_bpermute_b32 v113, v78, v97
	ds_bpermute_b32 v114, v78, v98
	ds_bpermute_b32 v115, v78, v99
	s_waitcnt lgkmcnt(15)
	v_add_f32_e32 v84, v84, v100
	s_waitcnt lgkmcnt(14)
	v_add_f32_e32 v85, v85, v101
	s_waitcnt lgkmcnt(13)
	v_add_f32_e32 v86, v86, v102
	s_waitcnt lgkmcnt(12)
	v_add_f32_e32 v87, v87, v103
	s_waitcnt lgkmcnt(11)
	v_add_f32_e32 v88, v88, v104
	s_waitcnt lgkmcnt(10)
	v_add_f32_e32 v89, v89, v105
	s_waitcnt lgkmcnt(9)
	v_add_f32_e32 v90, v90, v106
	s_waitcnt lgkmcnt(8)
	v_add_f32_e32 v91, v91, v107
	s_waitcnt lgkmcnt(7)
	v_add_f32_e32 v92, v92, v108
	s_waitcnt lgkmcnt(6)
	v_add_f32_e32 v93, v93, v109
	s_waitcnt lgkmcnt(5)
	v_add_f32_e32 v94, v94, v110
	s_waitcnt lgkmcnt(4)
	v_add_f32_e32 v95, v95, v111
	s_waitcnt lgkmcnt(3)
	v_add_f32_e32 v96, v96, v112
	s_waitcnt lgkmcnt(2)
	v_add_f32_e32 v97, v97, v113
	s_waitcnt lgkmcnt(1)
	v_add_f32_e32 v98, v98, v114
	s_waitcnt lgkmcnt(0)
	v_add_f32_e32 v99, v99, v115
	s_mov_b64 exec, 1
	ds_write_b128 v116, v[84:87]
	ds_write_b128 v116, v[88:91] offset:16
	ds_write_b128 v116, v[92:95] offset:32
	ds_write_b128 v116, v[96:99] offset:48
	s_mov_b64 exec, -1
	s_waitcnt lgkmcnt(0)
	s_barrier
	ds_read_b32 v128, v117
	ds_read_b32 v129, v117 offset:64
	ds_read_b32 v130, v117 offset:128
	ds_read_b32 v131, v117 offset:192
	ds_read_b32 v132, v117 offset:256
	ds_read_b32 v133, v117 offset:320
	ds_read_b32 v134, v117 offset:384
	ds_read_b32 v135, v117 offset:448
	s_waitcnt lgkmcnt(0)
	v_add_f32_e32 v128, v128, v129
	v_add_f32_e32 v130, v130, v131
	v_add_f32_e32 v132, v132, v133
	v_add_f32_e32 v134, v134, v135
	v_add_f32_e32 v128, v128, v130
	v_add_f32_e32 v132, v132, v134
	v_add_f32_e32 v128, v128, v132
	v_fmamk_f32 v128, v128, 0x3a000000, v79
	v_cmp_gt_f32_e32 vcc, s33, v128
	v_mul_f32_e32 v118, 0x4f800000, v128
	s_nop 1
	v_cndmask_b32_e32 v128, v128, v118, vcc
	v_sqrt_f32_e32 v118, v128
	s_nop 1
	v_add_u32_e32 v119, -1, v118
	v_fma_f32 v120, -v119, v118, v128
	v_cmp_ge_f32_e64 s[20:21], 0, v120
	v_add_u32_e32 v120, 1, v118
	s_nop 1
	v_cndmask_b32_e64 v119, v118, v119, s[20:21]
	v_fma_f32 v118, -v120, v118, v128
	v_cmp_lt_f32_e64 s[20:21], 0, v118
	s_nop 1
	v_cndmask_b32_e64 v118, v119, v120, s[20:21]
	v_mul_f32_e32 v119, 0x37800000, v118
	v_cndmask_b32_e32 v118, v118, v119, vcc
	v_cmp_class_f32_e32 vcc, v128, v80
	s_nop 1
	v_cndmask_b32_e32 v128, v118, v128, vcc
	v_div_scale_f32 v118, s[22:23], v128, v128, 1.0
	v_rcp_f32_e32 v119, v118
	s_nop 0
	v_fma_f32 v120, -v118, v119, 1.0
	v_fmac_f32_e32 v119, v120, v119
	v_div_scale_f32 v120, vcc, 1.0, v128, 1.0
	v_mul_f32_e32 v121, v120, v119
	v_fma_f32 v122, -v118, v121, v120
	v_fmac_f32_e32 v121, v122, v119
	v_fma_f32 v118, -v118, v121, v120
	v_div_fmas_f32 v118, v118, v119, v121
	v_div_fixup_f32 v118, v118, v128, 1.0
	v_readlane_b32 s12, v118, 0
	v_readlane_b32 s13, v118, 1
	v_readlane_b32 s14, v118, 2
	v_readlane_b32 s15, v118, 3
	v_readlane_b32 s16, v118, 4
	v_readlane_b32 s17, v118, 5
	v_readlane_b32 s18, v118, 6
	v_readlane_b32 s19, v118, 7
	s_nop 1
	v_mul_f32_e32 v4, s12, v4
	v_mul_f32_e32 v5, s12, v5
	v_mul_f32_e32 v6, s12, v6
	v_mul_f32_e32 v7, s12, v7
	v_pk_mul_f32 v[4:5], v[0:1], v[4:5]
	v_pk_mul_f32 v[6:7], v[2:3], v[6:7]
	v_lshl_add_u64 v[126:127], v[70:71], 0, s[24:25]
	global_store_dwordx4 v[126:127], v[4:7], off
	s_add_u32 s24, s24, 0x2000
	s_addc_u32 s25, s25, 0
	v_mul_f32_e32 v8, s13, v8
	v_mul_f32_e32 v9, s13, v9
	v_mul_f32_e32 v10, s13, v10
	v_mul_f32_e32 v11, s13, v11
	v_pk_mul_f32 v[8:9], v[0:1], v[8:9]
	v_pk_mul_f32 v[10:11], v[2:3], v[10:11]
	v_lshl_add_u64 v[126:127], v[70:71], 0, s[24:25]
	global_store_dwordx4 v[126:127], v[8:11], off
	s_add_u32 s24, s24, 0x2000
	s_addc_u32 s25, s25, 0
	v_mul_f32_e32 v12, s14, v12
	v_mul_f32_e32 v13, s14, v13
	v_mul_f32_e32 v14, s14, v14
	v_mul_f32_e32 v15, s14, v15
	v_pk_mul_f32 v[12:13], v[0:1], v[12:13]
	v_pk_mul_f32 v[14:15], v[2:3], v[14:15]
	v_lshl_add_u64 v[126:127], v[70:71], 0, s[24:25]
	global_store_dwordx4 v[126:127], v[12:15], off
	s_add_u32 s24, s24, 0x2000
	s_addc_u32 s25, s25, 0
	v_mul_f32_e32 v16, s15, v16
	v_mul_f32_e32 v17, s15, v17
	v_mul_f32_e32 v18, s15, v18
	v_mul_f32_e32 v19, s15, v19
	v_pk_mul_f32 v[16:17], v[0:1], v[16:17]
	v_pk_mul_f32 v[18:19], v[2:3], v[18:19]
	v_lshl_add_u64 v[126:127], v[70:71], 0, s[24:25]
	global_store_dwordx4 v[126:127], v[16:19], off
	s_add_u32 s24, s24, 0x2000
	s_addc_u32 s25, s25, 0
	v_mul_f32_e32 v20, s16, v20
	v_mul_f32_e32 v21, s16, v21
	v_mul_f32_e32 v22, s16, v22
	v_mul_f32_e32 v23, s16, v23
	v_pk_mul_f32 v[20:21], v[0:1], v[20:21]
	v_pk_mul_f32 v[22:23], v[2:3], v[22:23]
	v_lshl_add_u64 v[126:127], v[70:71], 0, s[24:25]
	global_store_dwordx4 v[126:127], v[20:23], off
	s_add_u32 s24, s24, 0x2000
	s_addc_u32 s25, s25, 0
	v_mul_f32_e32 v24, s17, v24
	v_mul_f32_e32 v25, s17, v25
	v_mul_f32_e32 v26, s17, v26
	v_mul_f32_e32 v27, s17, v27
	v_pk_mul_f32 v[24:25], v[0:1], v[24:25]
	v_pk_mul_f32 v[26:27], v[2:3], v[26:27]
	v_lshl_add_u64 v[126:127], v[70:71], 0, s[24:25]
	global_store_dwordx4 v[126:127], v[24:27], off
	s_add_u32 s24, s24, 0x2000
	s_addc_u32 s25, s25, 0
	v_mul_f32_e32 v28, s18, v28
	v_mul_f32_e32 v29, s18, v29
	v_mul_f32_e32 v30, s18, v30
	v_mul_f32_e32 v31, s18, v31
	v_pk_mul_f32 v[28:29], v[0:1], v[28:29]
	v_pk_mul_f32 v[30:31], v[2:3], v[30:31]
	v_lshl_add_u64 v[126:127], v[70:71], 0, s[24:25]
	global_store_dwordx4 v[126:127], v[28:31], off
	s_add_u32 s24, s24, 0x2000
	s_addc_u32 s25, s25, 0
	v_mul_f32_e32 v32, s19, v32
	v_mul_f32_e32 v33, s19, v33
	v_mul_f32_e32 v34, s19, v34
	v_mul_f32_e32 v35, s19, v35
	v_pk_mul_f32 v[32:33], v[0:1], v[32:33]
	v_pk_mul_f32 v[34:35], v[2:3], v[34:35]
	v_lshl_add_u64 v[126:127], v[70:71], 0, s[24:25]
	global_store_dwordx4 v[126:127], v[32:35], off
	s_add_u32 s24, s24, 0x2000
	s_addc_u32 s25, s25, 0
	v_readlane_b32 s12, v118, 8
	v_readlane_b32 s13, v118, 9
	v_readlane_b32 s14, v118, 10
	v_readlane_b32 s15, v118, 11
	v_readlane_b32 s16, v118, 12
	v_readlane_b32 s17, v118, 13
	v_readlane_b32 s18, v118, 14
	v_readlane_b32 s19, v118, 15
	s_nop 1
	v_mul_f32_e32 v36, s12, v36
	v_mul_f32_e32 v37, s12, v37
	v_mul_f32_e32 v38, s12, v38
	v_mul_f32_e32 v39, s12, v39
	v_pk_mul_f32 v[36:37], v[0:1], v[36:37]
	v_pk_mul_f32 v[38:39], v[2:3], v[38:39]
	v_lshl_add_u64 v[126:127], v[70:71], 0, s[24:25]
	global_store_dwordx4 v[126:127], v[36:39], off
	s_add_u32 s24, s24, 0x2000
	s_addc_u32 s25, s25, 0
	v_mul_f32_e32 v40, s13, v40
	v_mul_f32_e32 v41, s13, v41
	v_mul_f32_e32 v42, s13, v42
	v_mul_f32_e32 v43, s13, v43
	v_pk_mul_f32 v[40:41], v[0:1], v[40:41]
	v_pk_mul_f32 v[42:43], v[2:3], v[42:43]
	v_lshl_add_u64 v[126:127], v[70:71], 0, s[24:25]
	global_store_dwordx4 v[126:127], v[40:43], off
	s_add_u32 s24, s24, 0x2000
	s_addc_u32 s25, s25, 0
	v_mul_f32_e32 v44, s14, v44
	v_mul_f32_e32 v45, s14, v45
	v_mul_f32_e32 v46, s14, v46
	v_mul_f32_e32 v47, s14, v47
	v_pk_mul_f32 v[44:45], v[0:1], v[44:45]
	v_pk_mul_f32 v[46:47], v[2:3], v[46:47]
	v_lshl_add_u64 v[126:127], v[70:71], 0, s[24:25]
	global_store_dwordx4 v[126:127], v[44:47], off
	s_add_u32 s24, s24, 0x2000
	s_addc_u32 s25, s25, 0
	v_mul_f32_e32 v48, s15, v48
	v_mul_f32_e32 v49, s15, v49
	v_mul_f32_e32 v50, s15, v50
	v_mul_f32_e32 v51, s15, v51
	v_pk_mul_f32 v[48:49], v[0:1], v[48:49]
	v_pk_mul_f32 v[50:51], v[2:3], v[50:51]
	v_lshl_add_u64 v[126:127], v[70:71], 0, s[24:25]
	global_store_dwordx4 v[126:127], v[48:51], off
	s_add_u32 s24, s24, 0x2000
	s_addc_u32 s25, s25, 0
	v_mul_f32_e32 v52, s16, v52
	v_mul_f32_e32 v53, s16, v53
	v_mul_f32_e32 v54, s16, v54
	v_mul_f32_e32 v55, s16, v55
	v_pk_mul_f32 v[52:53], v[0:1], v[52:53]
	v_pk_mul_f32 v[54:55], v[2:3], v[54:55]
	v_lshl_add_u64 v[126:127], v[70:71], 0, s[24:25]
	global_store_dwordx4 v[126:127], v[52:55], off
	s_add_u32 s24, s24, 0x2000
	s_addc_u32 s25, s25, 0
	v_mul_f32_e32 v56, s17, v56
	v_mul_f32_e32 v57, s17, v57
	v_mul_f32_e32 v58, s17, v58
	v_mul_f32_e32 v59, s17, v59
	v_pk_mul_f32 v[56:57], v[0:1], v[56:57]
	v_pk_mul_f32 v[58:59], v[2:3], v[58:59]
	v_lshl_add_u64 v[126:127], v[70:71], 0, s[24:25]
	global_store_dwordx4 v[126:127], v[56:59], off
	s_add_u32 s24, s24, 0x2000
	s_addc_u32 s25, s25, 0
	v_mul_f32_e32 v60, s18, v60
	v_mul_f32_e32 v61, s18, v61
	v_mul_f32_e32 v62, s18, v62
	v_mul_f32_e32 v63, s18, v63
	v_pk_mul_f32 v[60:61], v[0:1], v[60:61]
	v_pk_mul_f32 v[62:63], v[2:3], v[62:63]
	v_lshl_add_u64 v[126:127], v[70:71], 0, s[24:25]
	global_store_dwordx4 v[126:127], v[60:63], off
	s_add_u32 s24, s24, 0x2000
	s_addc_u32 s25, s25, 0
	v_mul_f32_e32 v64, s19, v64
	v_mul_f32_e32 v65, s19, v65
	v_mul_f32_e32 v66, s19, v66
	v_mul_f32_e32 v67, s19, v67
	v_pk_mul_f32 v[64:65], v[0:1], v[64:65]
	v_pk_mul_f32 v[66:67], v[2:3], v[66:67]
	v_lshl_add_u64 v[126:127], v[70:71], 0, s[24:25]
	global_store_dwordx4 v[126:127], v[64:67], off
	s_add_u32 s24, s24, 0x2000
	s_addc_u32 s25, s25, 0
	s_waitcnt lgkmcnt(0)
	s_barrier
	s_add_i32 s2, s2, s34
	s_add_i32 s4, s4, s88
	s_cmpk_lt_i32 s2, 0x400
	s_cbranch_scc1 .Lnm_fin_loop
	s_branch .LBB0_1382
